# layer-1 small K.Wq / V.Wo GEMM units moved from the mixers phase into the idle tail slot of layer-1 FFN1-in (workgroups >= 128)
# baseline (speedup 1.0000x reference)
_ZN2mk6mk_fwdENS_4ArgsE:
	v_writelane_b32 v255, 0, 55
	s_load_dwordx8 s[36:43], s[0:1], 0xc0
	s_load_dwordx4 s[20:23], s[0:1], 0xe0
	s_load_dword s30, s[0:1], 0xf0
	v_and_b32_e32 v192, 0x3ff, v0
	s_add_u32 s4, s0, 0xe8
	v_readfirstlane_b32 s12, v192
	s_addc_u32 s5, s1, 0
	v_cmp_gt_u32_e32 vcc, 4, v192
	s_and_saveexec_b64 s[6:7], vcc
	v_lshl_add_u32 v1, v192, 2, 0
	v_add_u32_e32 v1, 0x22000, v1
	v_mov_b32_e32 v2, 0
	ds_write_b32 v1, v2
	s_or_b64 exec, exec, s[6:7]
	s_waitcnt lgkmcnt(0)
	s_sub_i32 s6, s21, s20
	s_mov_b32 s3, 0
	s_cmp_lt_i32 s6, 2
	v_cmp_eq_u32_e32 vcc, 0, v192
	s_barrier
	s_cbranch_scc1 .LBB0_8
	s_getreg_b32 s3, hwreg(HW_REG_XCC_ID, 0, 4)
	s_and_b32 s3, s3, 15
	s_and_saveexec_b64 s[6:7], vcc
	s_cbranch_execz .LBB0_7
	s_mov_b64 s[10:11], exec
	v_mbcnt_lo_u32_b32 v1, s10, 0
	v_mbcnt_hi_u32_b32 v1, s11, v1
	v_cmp_eq_u32_e32 vcc, 0, v1
	s_and_saveexec_b64 s[8:9], vcc
	s_cbranch_execz .LBB0_6
	s_lshl_b32 s13, s3, 8
	s_bcnt1_i32_b64 s10, s[10:11]
	v_mov_b32_e32 v2, s13
	v_mov_b32_e32 v3, s10
	global_atomic_add v2, v2, v3, s[42:43] offset:1024 sc0

.Lgmove_hook:
	v_writelane_b32 v248, s0, 0
	v_writelane_b32 v248, s1, 1
	v_writelane_b32 v248, s2, 2
	v_writelane_b32 v248, s3, 3
	v_writelane_b32 v248, s4, 4
	v_writelane_b32 v248, s5, 5
	v_writelane_b32 v248, s6, 6
	v_writelane_b32 v248, s7, 7
	v_writelane_b32 v248, s8, 8
	v_writelane_b32 v248, s9, 9
	v_writelane_b32 v248, s10, 10
	v_writelane_b32 v248, s11, 11
	v_writelane_b32 v248, s12, 12
	v_writelane_b32 v248, s13, 13
	v_writelane_b32 v248, s14, 14
	v_writelane_b32 v248, s15, 15
	v_writelane_b32 v248, s16, 16
	v_writelane_b32 v248, s17, 17
	v_writelane_b32 v248, s18, 18
	v_writelane_b32 v248, s19, 19
	v_writelane_b32 v248, s20, 20
	v_writelane_b32 v248, s21, 21
	v_writelane_b32 v248, s22, 22
	v_writelane_b32 v248, s23, 23
	v_writelane_b32 v248, s24, 24
	v_writelane_b32 v248, s25, 25
	v_writelane_b32 v248, s26, 26
	v_writelane_b32 v248, s27, 27
	v_writelane_b32 v248, s28, 28
	v_writelane_b32 v248, s29, 29
	v_writelane_b32 v248, s30, 30
	v_writelane_b32 v248, s31, 31
	v_writelane_b32 v248, s32, 32
	v_writelane_b32 v248, s33, 33
	v_writelane_b32 v248, s34, 34
	v_writelane_b32 v248, s35, 35
	v_writelane_b32 v248, s36, 36
	v_writelane_b32 v248, s37, 37
	v_writelane_b32 v248, s38, 38
	v_writelane_b32 v248, s39, 39
	v_writelane_b32 v248, s40, 40
	v_writelane_b32 v248, s41, 41
	v_writelane_b32 v248, s42, 42
	v_writelane_b32 v248, s43, 43
	v_writelane_b32 v248, s44, 44
	v_writelane_b32 v248, s45, 45
	v_writelane_b32 v248, s46, 46
	v_writelane_b32 v248, s47, 47
	v_writelane_b32 v248, s48, 48
	v_writelane_b32 v248, s49, 49
	v_writelane_b32 v248, s50, 50
	v_writelane_b32 v248, s51, 51
	v_writelane_b32 v248, s52, 52
	v_writelane_b32 v248, s53, 53
	v_writelane_b32 v248, s54, 54
	v_writelane_b32 v248, s55, 55
	v_writelane_b32 v248, s56, 56
	v_writelane_b32 v248, s57, 57
	v_writelane_b32 v248, s58, 58
	v_writelane_b32 v248, s59, 59
	v_writelane_b32 v248, s60, 60
	v_writelane_b32 v248, s61, 61
	v_writelane_b32 v248, s62, 62
	v_writelane_b32 v248, s63, 63
	v_writelane_b32 v249, s64, 0
	v_writelane_b32 v249, s65, 1
	v_writelane_b32 v249, s66, 2
	v_writelane_b32 v249, s67, 3
	v_writelane_b32 v249, s68, 4
	v_writelane_b32 v249, s69, 5
	v_writelane_b32 v249, s70, 6
	v_writelane_b32 v249, s71, 7
	v_writelane_b32 v249, s72, 8
	v_writelane_b32 v249, s73, 9
	v_writelane_b32 v249, s74, 10
	v_writelane_b32 v249, s75, 11
	v_writelane_b32 v249, s76, 12
	v_writelane_b32 v249, s77, 13
	v_writelane_b32 v249, s78, 14
	v_writelane_b32 v249, s79, 15
	v_writelane_b32 v249, s80, 16
	v_writelane_b32 v249, s81, 17
	v_writelane_b32 v249, s82, 18
	v_writelane_b32 v249, s83, 19
	v_writelane_b32 v249, s84, 20
	v_writelane_b32 v249, s85, 21
	v_writelane_b32 v249, s86, 22
	v_writelane_b32 v249, s87, 23
	v_writelane_b32 v249, s88, 24
	v_writelane_b32 v249, s89, 25
	v_writelane_b32 v249, s90, 26
	v_writelane_b32 v249, s91, 27
	v_writelane_b32 v249, s92, 28
	v_writelane_b32 v249, s93, 29
	v_writelane_b32 v249, s94, 30
	v_writelane_b32 v249, s95, 31
	v_writelane_b32 v249, s96, 32
	v_writelane_b32 v249, s97, 33
	v_writelane_b32 v249, s98, 34
	v_writelane_b32 v249, s99, 35
	v_writelane_b32 v249, vcc_lo, 36
	v_writelane_b32 v249, vcc_hi, 37
	s_mov_b64 s[2:3], exec
	s_mov_b32 s4, m0
	v_writelane_b32 v249, s2, 38
	v_writelane_b32 v249, s3, 39
	v_writelane_b32 v249, s4, 40
	v_writelane_b32 v255, 1, 55
	s_mov_b32 s30, 1
	s_mov_b32 s31, 0
	s_mov_b32 s1, 0
	s_waitcnt vmcnt(0) lgkmcnt(0)
	s_barrier
	s_branch .LBB0_495
.Lgmove_ret:
	v_writelane_b32 v255, 0, 55
	v_readlane_b32 s2, v249, 38
	v_readlane_b32 s3, v249, 39
	v_readlane_b32 s4, v249, 40
	s_mov_b64 exec, s[2:3]
	s_mov_b32 m0, s4
	v_readlane_b32 vcc_lo, v249, 36
	v_readlane_b32 vcc_hi, v249, 37
	v_readlane_b32 s0, v248, 0
	v_readlane_b32 s1, v248, 1
	v_readlane_b32 s2, v248, 2
	v_readlane_b32 s3, v248, 3
	v_readlane_b32 s4, v248, 4
	v_readlane_b32 s5, v248, 5
	v_readlane_b32 s6, v248, 6
	v_readlane_b32 s7, v248, 7
	v_readlane_b32 s8, v248, 8
	v_readlane_b32 s9, v248, 9
	v_readlane_b32 s10, v248, 10
	v_readlane_b32 s11, v248, 11
	v_readlane_b32 s12, v248, 12
	v_readlane_b32 s13, v248, 13
	v_readlane_b32 s14, v248, 14
	v_readlane_b32 s15, v248, 15
	v_readlane_b32 s16, v248, 16
	v_readlane_b32 s17, v248, 17
	v_readlane_b32 s18, v248, 18
	v_readlane_b32 s19, v248, 19
	v_readlane_b32 s20, v248, 20
	v_readlane_b32 s21, v248, 21
	v_readlane_b32 s22, v248, 22
	v_readlane_b32 s23, v248, 23
	v_readlane_b32 s24, v248, 24
	v_readlane_b32 s25, v248, 25
	v_readlane_b32 s26, v248, 26
	v_readlane_b32 s27, v248, 27
	v_readlane_b32 s28, v248, 28
	v_readlane_b32 s29, v248, 29
	v_readlane_b32 s30, v248, 30
	v_readlane_b32 s31, v248, 31
	v_readlane_b32 s32, v248, 32
	v_readlane_b32 s33, v248, 33
	v_readlane_b32 s34, v248, 34
	v_readlane_b32 s35, v248, 35
	v_readlane_b32 s36, v248, 36
	v_readlane_b32 s37, v248, 37
	v_readlane_b32 s38, v248, 38
	v_readlane_b32 s39, v248, 39
	v_readlane_b32 s40, v248, 40
	v_readlane_b32 s41, v248, 41
	v_readlane_b32 s42, v248, 42
	v_readlane_b32 s43, v248, 43
	v_readlane_b32 s44, v248, 44
	v_readlane_b32 s45, v248, 45
	v_readlane_b32 s46, v248, 46
	v_readlane_b32 s47, v248, 47
	v_readlane_b32 s48, v248, 48
	v_readlane_b32 s49, v248, 49
	v_readlane_b32 s50, v248, 50
	v_readlane_b32 s51, v248, 51
	v_readlane_b32 s52, v248, 52
	v_readlane_b32 s53, v248, 53
	v_readlane_b32 s54, v248, 54
	v_readlane_b32 s55, v248, 55
	v_readlane_b32 s56, v248, 56
	v_readlane_b32 s57, v248, 57
	v_readlane_b32 s58, v248, 58
	v_readlane_b32 s59, v248, 59
	v_readlane_b32 s60, v248, 60
	v_readlane_b32 s61, v248, 61
	v_readlane_b32 s62, v248, 62
	v_readlane_b32 s63, v248, 63
	v_readlane_b32 s64, v249, 0
	v_readlane_b32 s65, v249, 1
	v_readlane_b32 s66, v249, 2
	v_readlane_b32 s67, v249, 3
	v_readlane_b32 s68, v249, 4
	v_readlane_b32 s69, v249, 5
	v_readlane_b32 s70, v249, 6
	v_readlane_b32 s71, v249, 7
	v_readlane_b32 s72, v249, 8
	v_readlane_b32 s73, v249, 9
	v_readlane_b32 s74, v249, 10
	v_readlane_b32 s75, v249, 11
	v_readlane_b32 s76, v249, 12
	v_readlane_b32 s77, v249, 13
	v_readlane_b32 s78, v249, 14
	v_readlane_b32 s79, v249, 15
	v_readlane_b32 s80, v249, 16
	v_readlane_b32 s81, v249, 17
	v_readlane_b32 s82, v249, 18
	v_readlane_b32 s83, v249, 19
	v_readlane_b32 s84, v249, 20
	v_readlane_b32 s85, v249, 21
	v_readlane_b32 s86, v249, 22
	v_readlane_b32 s87, v249, 23
	v_readlane_b32 s88, v249, 24
	v_readlane_b32 s89, v249, 25
	v_readlane_b32 s90, v249, 26
	v_readlane_b32 s91, v249, 27
	v_readlane_b32 s92, v249, 28
	v_readlane_b32 s93, v249, 29
	v_readlane_b32 s94, v249, 30
	v_readlane_b32 s95, v249, 31
	v_readlane_b32 s96, v249, 32
	v_readlane_b32 s97, v249, 33
	v_readlane_b32 s98, v249, 34
	v_readlane_b32 s99, v249, 35
	s_branch .LBB0_139

.LBB0_498:
	s_lshl_b32 s2, s0, 4
	v_readlane_b32 s3, v252, 40
	s_sub_i32 s2, s3, s2
	s_ashr_i32 s3, s2, 31
	s_abs_i32 s2, s2
	v_readlane_b32 s4, v254, 17
	s_mul_hi_u32 s4, s2, s4
	v_readlane_b32 s5, v254, 19
	s_mul_i32 s4, s4, s5
	s_sub_i32 s2, s2, s4
	s_sub_i32 s4, s2, s5
	s_cmp_ge_u32 s2, s5
	s_cselect_b32 s2, s4, s2
	s_sub_i32 s4, s2, s5
	s_cmp_ge_u32 s2, s5
	s_cselect_b32 s2, s4, s2
	s_xor_b32 s2, s2, s3
	s_sub_i32 s60, s2, s3
	v_mov_b32_e32 v8, v192
	v_readlane_b32 s2, v255, 5
	v_readlane_b32 s5, v255, 55
	s_sub_i32 s2, s2, s5
	s_cmp_eq_u32 s2, 1
	s_cbranch_scc1 .LBB0_497
	s_cmp_gt_i32 s60, 15
	v_readfirstlane_b32 s6, v8
	s_cbranch_scc1 .LBB0_497
	s_ashr_i32 s61, s60, 31
	s_lshr_b32 s2, s61, 29
	s_add_i32 s7, s60, s2
	s_and_b32 s2, s7, -8
	s_sub_i32 s5, s60, s2
	s_cmp_gt_i32 s5, -1
	s_mov_b64 s[2:3], -1
	s_cbranch_scc0 .LBB0_501
	s_lshl_b32 s4, s5, 1
	s_mov_b64 s[2:3], 0

.LBB0_528:
	s_lshl_b32 s2, s0, 4
	v_readlane_b32 s3, v254, 18
	s_sub_i32 s2, s3, s2
	s_ashr_i32 s3, s2, 31
	s_abs_i32 s2, s2
	v_readlane_b32 s4, v254, 17
	s_mul_hi_u32 s4, s2, s4
	v_readlane_b32 s5, v254, 19
	s_mul_i32 s4, s4, s5
	s_sub_i32 s2, s2, s4
	s_sub_i32 s4, s2, s5
	s_cmp_ge_u32 s2, s5
	s_cselect_b32 s2, s4, s2
	s_sub_i32 s4, s2, s5
	s_cmp_ge_u32 s2, s5
	s_cselect_b32 s2, s4, s2
	s_xor_b32 s2, s2, s3
	s_sub_i32 s60, s2, s3
	v_mov_b32_e32 v8, v192
	v_readlane_b32 s2, v255, 5
	v_readlane_b32 s5, v255, 55
	s_sub_i32 s2, s2, s5
	s_cmp_eq_u32 s2, 1
	s_cbranch_scc1 .LBB0_527
	s_cmp_gt_i32 s60, 15
	v_readfirstlane_b32 s6, v8
	s_cbranch_scc1 .LBB0_527
	s_ashr_i32 s61, s60, 31
	s_lshr_b32 s2, s61, 29
	s_add_i32 s7, s60, s2
	s_and_b32 s2, s7, -8
	s_sub_i32 s5, s60, s2
	s_cmp_gt_i32 s5, -1
	s_mov_b64 s[2:3], -1
	s_cbranch_scc0 .LBB0_531
	s_lshl_b32 s4, s5, 1
	s_mov_b64 s[2:3], 0

.LBB0_551:
	v_readlane_b32 s0, v255, 55
	s_cmp_eq_u32 s0, 1
	s_cbranch_scc1 .Lgmove_ret
	v_readlane_b32 s0, v255, 0
	s_add_i32 s0, s0, 5
	s_cmp_lt_i32 s0, s21
	s_cbranch_scc0 .LBB0_562
	s_waitcnt vmcnt(0)
	s_waitcnt vmcnt(0) lgkmcnt(0)
	s_barrier
	s_mov_b64 s[2:3], exec
	v_readlane_b32 s4, v254, 56
	v_readlane_b32 s5, v254, 57
	v_readlane_b32 s60, v254, 62
	s_and_b64 s[4:5], s[2:3], s[4:5]
	v_readlane_b32 s61, v254, 63
	s_mov_b64 exec, s[4:5]
	s_cbranch_execz .LBB0_600
	v_readlane_b32 s4, v254, 48
	s_waitcnt vmcnt(0) expcnt(0) lgkmcnt(0)
	s_nop 0
	v_mov_b32_e32 v0, s4
	ds_read_b32 v2, v0
	v_readlane_b32 s4, v254, 49
	s_waitcnt lgkmcnt(0)
	v_cmp_ne_u32_e32 vcc, 0, v2
	v_mov_b32_e32 v0, s4
	ds_read_b32 v0, v0
	s_cbranch_vccnz .LBB0_568
	s_mov_b32 s8, 1
	s_branch .LBB0_556
